# attention loop head pinned to a 64-byte boundary (.p2align 6 before the loop label)
# baseline (speedup 1.0000x reference)
; __device__ __forceinline__ void attn_unit(LAS char* lds, const bf16_t* Qp, const bf16_t* KVp, const bf16_t* KRp, int ntiles, bf16_t* Yp, bool dry) {
;     ...
;     const int krow = tid >> 3, kc = tid & 7, rrow = tid >> 2, rc = tid & 3;
;     const bf16_t* gk = KVp + (size_t)krow * 1024 + kc * 8;
;     const bf16_t* gv = gk + 512;
;     const bf16_t* gr = KRp + (size_t)rrow * 32 + rc * 8;
;     const int lk = krow * AK_PITCH + kc * 16, lr = rrow * AK_PITCH + 128 + rc * 16, lv = (kc >> 2) * 4096 + krow * 64 + (kc & 3) * 16;
;     const bool rth = tid < 256;
;     u32x4 skA, svA, srA = {0u, 0u, 0u, 0u}, skB, svB, srB = {0u, 0u, 0u, 0u};
.Latt_iter:
	s_waitcnt vmcnt(0)
	v_xor_b32_e32 v82, 0x80000000, v189
	v_mov_b32_e32 v83, v82
	v_mov_b32_e32 v84, v82
	v_mov_b32_e32 v85, v82
	v_mov_b32_e32 v86, v82
	v_mov_b32_e32 v87, v82
	v_mov_b32_e32 v88, v82
	v_mov_b32_e32 v89, v82
	v_mov_b32_e32 v90, v82
	v_mov_b32_e32 v91, v82
	v_mov_b32_e32 v92, v82
	v_mov_b32_e32 v93, v82
	v_mov_b32_e32 v94, v82
	v_mov_b32_e32 v95, v82
	v_mov_b32_e32 v96, v82
	v_mov_b32_e32 v97, v82
	s_ashr_i32 s14, s8, 6
	s_mul_i32 s2, s14, 0x480000
	s_bfe_u32 s15, s8, 0x30003
	s_lshl_b32 s15, s15, 7
	s_add_i32 s2, s2, s15
	s_add_u32 s2, s2, 0x2f440000
	s_add_u32 s2, s88, s2
	s_addc_u32 s3, s89, 0
	s_mul_i32 s16, s14, 0x24000
	s_add_u32 s16, s16, 0x3cc02000
	s_add_u32 s16, s88, s16
	s_addc_u32 s17, s89, 0
	v_mov_b32_e32 v180, 0x40000
	v_mov_b32_e32 v181, 0x2000
	v_mov_b32_e32 v212, v182
	v_cmp_lt_u32_e32 vcc, 831, v212
	v_cndmask_b32_e64 v213, 0, 1, vcc
	v_mul_u32_u24_e32 v214, 832, v213
	v_sub_u32_e32 v212, v212, v214
	v_mul_u32_u24_e32 v214, 5042, v212
	v_lshrrev_b32_e32 v214, 16, v214
	v_mul_u32_u24_e32 v215, 13, v214
	v_sub_u32_e32 v215, v212, v215
	v_cmp_eq_u32_e32 vcc, 12, v215
	v_cndmask_b32_e64 v215, v215, 0, vcc
	v_lshlrev_b32_e32 v150, 17, v213
	v_lshl_add_u32 v150, v214, 11, v150
	v_lshl_add_u32 v150, v215, 4, v150
	v_lshlrev_b32_e32 v151, 12, v213
	v_lshl_add_u32 v151, v214, 6, v151
	v_lshl_add_u32 v151, v215, 4, v151
	v_add_u32_e32 v151, 0xffffff80, v151
	v_cmp_lt_u32_e64 s[14:15], 7, v215
	v_cndmask_b32_e64 v150, v150, v151, s[14:15]
	v_mov_b32_e32 v152, s2
	v_mov_b32_e32 v153, s3
	v_mov_b32_e32 v178, s16
	v_mov_b32_e32 v179, s17
	v_cndmask_b32_e64 v152, v152, v178, s[14:15]
	v_cndmask_b32_e64 v153, v153, v179, s[14:15]
	v_cndmask_b32_e64 v142, v180, v181, s[14:15]
	v_mov_b32_e32 v143, 0
	v_add_co_u32_e32 v130, vcc, v150, v152
	s_nop 1
	v_addc_co_u32_e32 v131, vcc, 0, v153, vcc
	v_add_u32_e32 v212, 512, v182
	v_cmp_lt_u32_e32 vcc, 831, v212
	v_cndmask_b32_e64 v213, 0, 1, vcc
	v_mul_u32_u24_e32 v214, 832, v213
	v_sub_u32_e32 v212, v212, v214
	v_mul_u32_u24_e32 v214, 5042, v212
	v_lshrrev_b32_e32 v214, 16, v214
	v_mul_u32_u24_e32 v215, 13, v214
	v_sub_u32_e32 v215, v212, v215
	v_cmp_eq_u32_e32 vcc, 12, v215
	v_cndmask_b32_e64 v215, v215, 0, vcc
	v_lshlrev_b32_e32 v150, 17, v213
	v_lshl_add_u32 v150, v214, 11, v150
	v_lshl_add_u32 v150, v215, 4, v150
	v_lshlrev_b32_e32 v151, 12, v213
	v_lshl_add_u32 v151, v214, 6, v151
	v_lshl_add_u32 v151, v215, 4, v151
	v_add_u32_e32 v151, 0xffffff80, v151
	v_cmp_lt_u32_e64 s[14:15], 7, v215
	v_cndmask_b32_e64 v150, v150, v151, s[14:15]
	v_mov_b32_e32 v152, s2
	v_mov_b32_e32 v153, s3
	v_mov_b32_e32 v178, s16
	v_mov_b32_e32 v179, s17
	v_cndmask_b32_e64 v152, v152, v178, s[14:15]
	v_cndmask_b32_e64 v153, v153, v179, s[14:15]
	v_cndmask_b32_e64 v144, v180, v181, s[14:15]
	v_mov_b32_e32 v145, 0
	v_add_co_u32_e32 v132, vcc, v150, v152
	s_nop 1
	v_addc_co_u32_e32 v133, vcc, 0, v153, vcc
	v_add_u32_e32 v212, 1024, v182
	v_cmp_lt_u32_e32 vcc, 831, v212
	v_cndmask_b32_e64 v213, 0, 1, vcc
	v_mul_u32_u24_e32 v214, 832, v213
	v_sub_u32_e32 v212, v212, v214
	v_mul_u32_u24_e32 v214, 5042, v212
	v_lshrrev_b32_e32 v214, 16, v214
	v_mul_u32_u24_e32 v215, 13, v214
	v_sub_u32_e32 v215, v212, v215
	v_cmp_eq_u32_e32 vcc, 12, v215
	v_cndmask_b32_e64 v215, v215, 0, vcc
	v_lshlrev_b32_e32 v150, 17, v213
	v_lshl_add_u32 v150, v214, 11, v150
	v_lshl_add_u32 v150, v215, 4, v150
	v_lshlrev_b32_e32 v151, 12, v213
	v_lshl_add_u32 v151, v214, 6, v151
	v_lshl_add_u32 v151, v215, 4, v151
	v_add_u32_e32 v151, 0xffffff80, v151
	v_cmp_lt_u32_e64 s[14:15], 7, v215
	v_cndmask_b32_e64 v150, v150, v151, s[14:15]
	v_mov_b32_e32 v152, s2
	v_mov_b32_e32 v153, s3
	v_mov_b32_e32 v178, s16
	v_mov_b32_e32 v179, s17
	v_cndmask_b32_e64 v152, v152, v178, s[14:15]
	v_cndmask_b32_e64 v153, v153, v179, s[14:15]
	v_cndmask_b32_e64 v146, v180, v181, s[14:15]
	v_mov_b32_e32 v147, 0
	v_add_co_u32_e32 v134, vcc, v150, v152
	s_nop 1
	v_addc_co_u32_e32 v135, vcc, 0, v153, vcc
	v_add_u32_e32 v212, 1536, v182
	v_cmp_lt_u32_e32 vcc, 831, v212
	v_cndmask_b32_e64 v213, 0, 1, vcc
	v_mul_u32_u24_e32 v214, 832, v213
	v_sub_u32_e32 v212, v212, v214
	v_mul_u32_u24_e32 v214, 5042, v212
	v_lshrrev_b32_e32 v214, 16, v214
	v_mul_u32_u24_e32 v215, 13, v214
	v_sub_u32_e32 v215, v212, v215
	v_cmp_eq_u32_e32 vcc, 12, v215
	v_cndmask_b32_e64 v215, v215, 0, vcc
	v_lshlrev_b32_e32 v150, 17, v213
	v_lshl_add_u32 v150, v214, 11, v150
	v_lshl_add_u32 v150, v215, 4, v150
	v_lshlrev_b32_e32 v151, 12, v213
	v_lshl_add_u32 v151, v214, 6, v151
	v_lshl_add_u32 v151, v215, 4, v151
	v_add_u32_e32 v151, 0xffffff80, v151
	v_cmp_lt_u32_e64 s[14:15], 7, v215
	v_cndmask_b32_e64 v150, v150, v151, s[14:15]
	v_mov_b32_e32 v152, s2
	v_mov_b32_e32 v153, s3
	v_mov_b32_e32 v178, s16
	v_mov_b32_e32 v179, s17
	v_cndmask_b32_e64 v152, v152, v178, s[14:15]
	v_cndmask_b32_e64 v153, v153, v179, s[14:15]
	v_cndmask_b32_e64 v148, v180, v181, s[14:15]
	v_mov_b32_e32 v149, 0
	v_add_co_u32_e32 v136, vcc, v150, v152
	s_nop 1
	v_addc_co_u32_e32 v137, vcc, 0, v153, vcc
	v_bfe_u32 v212, v182, 6, 2
	v_bfe_u32 v213, v182, 2, 4
	v_lshl_add_u32 v212, v212, 4, v213
	v_bfe_u32 v213, v182, 8, 1
	v_and_b32_e32 v214, 3, v182
	v_lshl_add_u32 v213, v213, 2, v214
	v_lshlrev_b32_e32 v212, 11, v212
	v_lshl_add_u32 v212, v213, 4, v212
	v_add_u32_e32 v212, 0x400, v212
	v_mov_b32_e32 v213, s3
	v_add_co_u32_e32 v138, vcc, s2, v212
	s_nop 1
	v_addc_co_u32_e32 v139, vcc, 0, v213, vcc
	v_add_co_u32_e32 v140, vcc, 0x20000, v138
	s_nop 1
	v_addc_co_u32_e32 v141, vcc, 0, v139, vcc
	.p2align 6
